# cross-attention unit loop: the loop-top vmcnt(0) moved ahead of the ticket atomic so the atomic stays in flight through the K/V fill (on top of v039)
# speedup vs baseline: 1.0067x; 1.0067x over previous
; DI void xattn_unit(const Args& a, const Frame& F, int l, int unit) {
;     const bf16* Q = (const bf16*)(a.ws + WS_Q); bf16* OX = (bf16*)(a.ws + WS_OX);
;     int lane = F.lane, tid = F.tid; asm volatile("" : "+v"(lane), "+v"(tid));
;     const int fr = lane & 15, fq = lane >> 4;
;     const bool prompt = unit < 128;
;     int b, h, row0, nrg;
;     if (prompt) { b = unit >> 5; h = (unit >> 3) & 3; row0 = b * TP + (unit & 7) * 512; nrg = 32; }
;     else { const int u = unit - 128; b = u >> 2; h = u & 3; row0 = NP + b * 64; nrg = 4; }
;     bf16x8 qc[4];
.LBB0_2026:
	s_waitcnt vmcnt(0)
	v_mov_b32_e32 v3, 0
	s_and_saveexec_b64 s[0:1], s[36:37]
	s_cbranch_execz .LBB0_2030
	s_mov_b64 s[8:9], exec
	v_mbcnt_lo_u32_b32 v3, s8, 0
	v_mbcnt_hi_u32_b32 v3, s9, v3
	v_cmp_eq_u32_e32 vcc, 0, v3
	s_and_saveexec_b64 s[6:7], vcc
	s_cbranch_execz .LBB0_2029
	s_bcnt1_i32_b64 s8, s[8:9]
	v_mov_b32_e32 v4, s8
	global_atomic_add v3, v2, v4, s[4:5] sc0

; DI void xattn_unit(const Args& a, const Frame& F, int l, int unit) {
;     ...
;     const bool prompt = unit < 128;
;     int b, h, row0, nrg;
;     if (prompt) { b = unit >> 5; h = (unit >> 3) & 3; row0 = b * TP + (unit & 7) * 512; nrg = 32; }
;     else { const int u = unit - 128; b = u >> 2; h = u & 3; row0 = NP + b * 64; nrg = 4; }
;     bf16x8 qc[4];
.LBB0_2030:
	s_or_b64 exec, exec, s[0:1]
	s_cmpk_gt_i32 s14, 0x7f
	s_cselect_b64 s[0:1], -1, 0
	v_mov_b32_e32 v95, v160
	v_mov_b32_e32 v8, v0
	s_mov_b64 s[6:7], -1
	s_and_b64 vcc, exec, s[0:1]
	s_cbranch_vccz .LBB0_2032
	s_add_i32 s6, s14, 0xffffff80
	s_lshr_b32 s13, s6, 2
	s_lshl_b32 s6, s13, 6
	s_add_i32 s9, s6, 0x4000
	s_mov_b64 s[6:7], 0
